# GEMM phase prologues: second staging batch issued right behind the first, wait+barrier after both (same completion guarantees)
# speedup vs baseline: 1.0113x; 1.0113x over previous
; #define PG8_STAGE(bufoff, gbase, voff) do { _Pragma("unroll") for (int _i = 0; _i < 2; ++_i) \
;         __builtin_amdgcn_global_load_lds((const unsigned*)((const char*)(gbase) + (voff)[_i]), (LAS unsigned*)(lds + (bufoff) + ldsw + _i * 8192), 16, 0, 0); } while (0)
; #define PG8_WAIT_V(n) asm volatile("s_waitcnt vmcnt(" #n ")" ::: "memory")
; #define PG8_BAR __builtin_amdgcn_s_barrier()
; template <class Epi>
; __device__ __forceinline__ void gemm_phase(LAS unsigned char* lds, const Gemm g, const StaticOrder& S, const Epi& E, const int tid) {
;     ...
;     PG8_STAGE(PG8_SB(0, 0), cB, voffB); PG8_STAGE(PG8_SB(0, 1), cB + hstepB, voffB); PG8_STAGE(PG8_SA(0, 0), cA, voffA); PG8_STAGE(PG8_SA(0, 1), cA + hstepA, voffA);
;     if (wr == 1) PG8_BAR;
;     PG8_WAIT_V(2); PG8_BAR;
;     PG8_STAGE(PG8_SB(1, 0), cB + kstep, voffB); PG8_STAGE(PG8_SA(1, 0), cA + kstep, voffA); PG8_STAGE(PG8_SB(1, 1), cB + hstepB + kstep, voffB);
;     PG8_WAIT_V(6); PG8_BAR;
.LBB0_170:
	v_readlane_b32 s6, v255, 1
	v_readlane_b32 s7, v255, 2
	s_add_u32 s20, s6, 0x17c00000
	s_addc_u32 s21, s7, 0
	s_add_u32 s22, s6, 0x1800000
	s_addc_u32 s23, s7, 0
	s_lshr_b32 s5, s5, 26
	s_and_b32 s0, s0, 3
	s_add_i32 s5, s4, s5
	s_ashr_i32 s48, s5, 6
	s_lshl_b32 s49, s1, 6
	s_lshl_b32 s1, s1, 13
	s_lshl_b32 s50, s0, 5
	s_lshl_b32 s5, s0, 12
	s_add_u32 s74, s6, 0x1600000
	s_addc_u32 s75, s7, 0
	s_add_i32 m0, s44, 0x18000
	v_lshl_add_u64 v[2:3], v[2:3], 0, s[80:81]
	global_load_lds_dwordx4 v[2:3], off
	v_lshl_add_u64 v[2:3], v[4:5], 0, s[80:81]
	s_add_i32 m0, s44, 0x1a000
	s_add_i32 s51, s44, 0x8000
	global_load_lds_dwordx4 v[2:3], off
	v_lshl_add_u64 v[2:3], v[10:11], 0, s[80:81]
	s_mov_b32 m0, s51
	s_add_i32 s52, s44, 0xa000
	global_load_lds_dwordx4 v[2:3], off
	v_lshl_add_u64 v[2:3], v[12:13], 0, s[80:81]
	s_mov_b32 m0, s52
	s_movk_i32 s6, 0x3c0
	global_load_lds_dwordx4 v[2:3], off
	s_add_i32 m0, s44, 0x1c000
	v_lshl_add_u64 v[2:3], v[6:7], 0, s[80:81]
	global_load_lds_dwordx4 v[2:3], off
	v_lshl_add_u64 v[2:3], v[8:9], 0, s[80:81]
	s_add_i32 m0, s44, 0x1e000
	s_cmp_gt_i32 s4, 63
	global_load_lds_dwordx4 v[2:3], off
	s_waitcnt vmcnt(8)
	s_barrier
	v_and_b32_e32 v2, 48, v251
	v_lshlrev_b32_e32 v3, 6, v251
	v_and_or_b32 v2, v3, s6, v2
	v_lshlrev_b32_e32 v3, 2, v251
	v_and_b32_e32 v3, 32, v3
	v_bitop3_b32 v4, v2, s1, v3 bitop3:0xde
	v_bitop3_b32 v168, s5, v2, v3 bitop3:0xf6
	v_add_u32_e32 v2, v19, v17
	s_cselect_b64 s[96:97], -1, 0
	s_add_i32 s53, s48, -2
	v_add_lshl_u32 v2, v2, v18, 1
	v_mov_b32_e32 v3, v1
	s_waitcnt vmcnt(6)
	s_cmpk_lt_u32 s30, 0x100
	v_lshl_add_u64 v[148:149], s[10:11], 0, v[2:3]
	v_add_u32_e32 v2, v16, v14
	s_cselect_b64 s[28:29], -1, 0
	s_and_b32 s1, s30, 0xffffff00
	s_lshl_b32 s0, s0, 6
	v_add_lshl_u32 v2, v2, v15, 1
	s_or_b32 s54, s0, s1
	v_lshl_add_u64 v[150:151], s[10:11], 0, v[2:3]
	s_mov_b32 s55, 0
	v_add_u32_e32 v169, 0, v4
	s_barrier
	s_branch .LBB0_173

; #define PG8_STAGE(bufoff, gbase, voff) do { _Pragma("unroll") for (int _i = 0; _i < 2; ++_i) \
;         __builtin_amdgcn_global_load_lds((const unsigned*)((const char*)(gbase) + (voff)[_i]), (LAS unsigned*)(lds + (bufoff) + ldsw + _i * 8192), 16, 0, 0); } while (0)
; #define PG8_WAIT_V(n) asm volatile("s_waitcnt vmcnt(" #n ")" ::: "memory")
; #define PG8_BAR __builtin_amdgcn_s_barrier()
; template <class Epi>
; __device__ __forceinline__ void gemm_phase(LAS unsigned char* lds, const Gemm g, const StaticOrder& S, const Epi& E, const int tid) {
;     ...
;     PG8_STAGE(PG8_SB(0, 0), cB, voffB); PG8_STAGE(PG8_SB(0, 1), cB + hstepB, voffB); PG8_STAGE(PG8_SA(0, 0), cA, voffA); PG8_STAGE(PG8_SA(0, 1), cA + hstepA, voffA);
;     if (wr == 1) PG8_BAR;
;     PG8_WAIT_V(2); PG8_BAR;
;     PG8_STAGE(PG8_SB(1, 0), cB + kstep, voffB); PG8_STAGE(PG8_SA(1, 0), cA + kstep, voffA); PG8_STAGE(PG8_SB(1, 1), cB + hstepB + kstep, voffB);
;     PG8_WAIT_V(6); PG8_BAR;
.LBB0_283:
	s_and_b32 s45, s0, 3
	s_lshr_b32 s0, s5, 26
	s_add_i32 s0, s4, s0
	s_ashr_i32 s46, s0, 6
	s_lshl_b32 s47, s1, 6
	s_lshl_b32 s5, s1, 13
	s_lshl_b32 s48, s45, 5
	s_lshl_b32 s24, s45, 12
	s_lshl_b64 s[0:1], s[6:7], 2
	s_mov_b64 s[6:7], s[74:75]
	s_add_u32 s22, s6, s0
	s_addc_u32 s23, s7, s1
	s_add_i32 m0, s38, 0x18000
	v_lshl_add_u64 v[2:3], v[2:3], 0, s[80:81]
	global_load_lds_dwordx4 v[2:3], off
	v_lshl_add_u64 v[2:3], v[4:5], 0, s[80:81]
	s_add_i32 m0, s38, 0x1a000
	s_add_i32 s49, s38, 0x8000
	global_load_lds_dwordx4 v[2:3], off
	v_lshl_add_u64 v[2:3], v[10:11], 0, s[80:81]
	s_mov_b32 m0, s49
	s_add_i32 s50, s38, 0xa000
	global_load_lds_dwordx4 v[2:3], off
	v_lshl_add_u64 v[2:3], v[12:13], 0, s[80:81]
	s_mov_b32 m0, s50
	s_movk_i32 s0, 0x3c0
	global_load_lds_dwordx4 v[2:3], off
	s_add_i32 m0, s38, 0x1c000
	v_lshl_add_u64 v[2:3], v[6:7], 0, s[80:81]
	global_load_lds_dwordx4 v[2:3], off
	v_lshl_add_u64 v[2:3], v[8:9], 0, s[80:81]
	s_add_i32 m0, s38, 0x1e000
	s_cmp_gt_i32 s4, 63
	global_load_lds_dwordx4 v[2:3], off
	s_waitcnt vmcnt(8)
	s_barrier
	v_and_b32_e32 v2, 48, v251
	v_lshlrev_b32_e32 v3, 6, v251
	v_and_or_b32 v2, v3, s0, v2
	v_lshlrev_b32_e32 v3, 2, v251
	v_and_b32_e32 v3, 32, v3
	v_bitop3_b32 v4, v2, s5, v3 bitop3:0xde
	v_bitop3_b32 v248, s24, v2, v3 bitop3:0xf6
	v_add_u32_e32 v2, v19, v17
	v_add_lshl_u32 v2, v2, v18, 1
	v_mov_b32_e32 v3, v1
	s_waitcnt vmcnt(6)
	s_cselect_b64 s[24:25], -1, 0
	s_add_i32 s51, s46, -2
	v_lshl_add_u64 v[208:209], s[12:13], 0, v[2:3]
	v_add_u32_e32 v2, v16, v14
	s_cmpk_lt_u32 s26, 0x100
	v_add_lshl_u32 v2, v2, v15, 1
	s_cselect_b64 s[26:27], -1, 0
	s_ashr_i32 s52, s84, 31
	v_lshl_add_u64 v[210:211], s[12:13], 0, v[2:3]
	s_mov_b32 s53, 0
	v_add_u32_e32 v194, 0, v4
	s_barrier
	s_branch .LBB0_286

; #define PG8_STAGE(bufoff, gbase, voff) do { _Pragma("unroll") for (int _i = 0; _i < 2; ++_i) \
;         __builtin_amdgcn_global_load_lds((const unsigned*)((const char*)(gbase) + (voff)[_i]), (LAS unsigned*)(lds + (bufoff) + ldsw + _i * 8192), 16, 0, 0); } while (0)
; #define PG8_WAIT_V(n) asm volatile("s_waitcnt vmcnt(" #n ")" ::: "memory")
; #define PG8_BAR __builtin_amdgcn_s_barrier()
; template <class Epi>
; __device__ __forceinline__ void gemm_phase(LAS unsigned char* lds, const Gemm g, const StaticOrder& S, const Epi& E, const int tid) {
;     ...
;     PG8_STAGE(PG8_SB(0, 0), cB, voffB); PG8_STAGE(PG8_SB(0, 1), cB + hstepB, voffB); PG8_STAGE(PG8_SA(0, 0), cA, voffA); PG8_STAGE(PG8_SA(0, 1), cA + hstepA, voffA);
;     if (wr == 1) PG8_BAR;
;     PG8_WAIT_V(2); PG8_BAR;
;     PG8_STAGE(PG8_SB(1, 0), cB + kstep, voffB); PG8_STAGE(PG8_SA(1, 0), cA + kstep, voffA); PG8_STAGE(PG8_SB(1, 1), cB + hstepB + kstep, voffB);
;     PG8_WAIT_V(6); PG8_BAR;
.LBB0_333:
	s_mov_b64 s[4:5], s[74:75]
	s_add_u32 s22, s4, 0x1000000
	s_addc_u32 s23, s5, 0
	s_add_u32 s48, s4, 0x7bc3800
	s_addc_u32 s49, s5, 0
	s_add_i32 m0, s44, 0x18000
	v_lshl_add_u64 v[2:3], v[2:3], 0, s[80:81]
	global_load_lds_dwordx4 v[2:3], off
	v_lshl_add_u64 v[2:3], v[4:5], 0, s[80:81]
	s_add_i32 m0, s44, 0x1a000
	s_add_i32 s50, s44, 0x8000
	global_load_lds_dwordx4 v[2:3], off
	v_lshl_add_u64 v[2:3], v[10:11], 0, s[80:81]
	s_mov_b32 m0, s50
	s_add_i32 s51, s44, 0xa000
	global_load_lds_dwordx4 v[2:3], off
	v_lshl_add_u64 v[2:3], v[12:13], 0, s[80:81]
	s_mov_b32 m0, s51
	s_and_b32 s52, s0, 3
	global_load_lds_dwordx4 v[2:3], off
	s_add_i32 m0, s44, 0x1c000
	v_lshl_add_u64 v[2:3], v[6:7], 0, s[80:81]
	global_load_lds_dwordx4 v[2:3], off
	v_lshl_add_u64 v[2:3], v[8:9], 0, s[80:81]
	s_add_i32 m0, s44, 0x1e000
	s_lshr_b32 s0, s11, 26
	global_load_lds_dwordx4 v[2:3], off
	s_waitcnt vmcnt(8)
	s_barrier
	v_and_b32_e32 v2, 48, v251
	v_lshlrev_b32_e32 v3, 6, v251
	s_movk_i32 s4, 0x3c0
	s_add_i32 s0, s10, s0
	v_and_or_b32 v2, v3, s4, v2
	v_lshlrev_b32_e32 v3, 2, v251
	s_ashr_i32 s53, s0, 6
	s_lshl_b32 s0, s1, 13
	v_and_b32_e32 v3, 32, v3
	s_lshl_b32 s54, s1, 6
	v_bitop3_b32 v4, v2, s0, v3 bitop3:0xde
	s_lshl_b32 s55, s52, 5
	s_lshl_b32 s0, s52, 12
	s_cmp_gt_i32 s10, 63
	s_cselect_b64 s[10:11], -1, 0
	s_add_i32 s56, s53, -2
	s_cmpk_lt_u32 s24, 0x100
	v_bitop3_b32 v234, s0, v2, v3 bitop3:0xf6
	s_cselect_b64 s[24:25], -1, 0
	s_lshl_b32 s0, s1, 2
	v_add_u32_e32 v2, v19, v17
	s_or_b32 s0, s0, s52
	v_add_lshl_u32 v2, v2, v18, 1
	v_mov_b32_e32 v3, v1
	s_waitcnt vmcnt(6)
	s_cmp_eq_u32 s0, 0
	v_lshl_add_u64 v[208:209], s[12:13], 0, v[2:3]
	v_add_u32_e32 v2, v16, v14
	s_cselect_b64 s[26:27], -1, 0
	s_cmp_lt_i32 s0, 4
	v_add_lshl_u32 v2, v2, v15, 1
	s_mov_b32 s57, 0
	s_cselect_b64 s[28:29], -1, 0
	s_lshl_b32 s58, s0, 6
	s_ashr_i32 s59, s84, 31
	v_lshl_add_u64 v[210:211], s[12:13], 0, v[2:3]
	v_add_u32_e32 v235, 0, v4
	s_barrier
	s_branch .LBB0_336

; #define PG8_STAGE(bufoff, gbase, voff) do { _Pragma("unroll") for (int _i = 0; _i < 2; ++_i) \
;         __builtin_amdgcn_global_load_lds((const unsigned*)((const char*)(gbase) + (voff)[_i]), (LAS unsigned*)(lds + (bufoff) + ldsw + _i * 8192), 16, 0, 0); } while (0)
; #define PG8_WAIT_V(n) asm volatile("s_waitcnt vmcnt(" #n ")" ::: "memory")
; #define PG8_BAR __builtin_amdgcn_s_barrier()
; template <class Epi>
; __device__ __forceinline__ void gemm_phase(LAS unsigned char* lds, const Gemm g, const StaticOrder& S, const Epi& E, const int tid) {
;     ...
;     PG8_STAGE(PG8_SB(0, 0), cB, voffB); PG8_STAGE(PG8_SB(0, 1), cB + hstepB, voffB); PG8_STAGE(PG8_SA(0, 0), cA, voffA); PG8_STAGE(PG8_SA(0, 1), cA + hstepA, voffA);
;     if (wr == 1) PG8_BAR;
;     PG8_WAIT_V(2); PG8_BAR;
;     PG8_STAGE(PG8_SB(1, 0), cB + kstep, voffB); PG8_STAGE(PG8_SA(1, 0), cA + kstep, voffA); PG8_STAGE(PG8_SB(1, 1), cB + hstepB + kstep, voffB);
;     PG8_WAIT_V(6); PG8_BAR;
.LBB0_416:
	s_lshr_b32 s5, s5, 26
	s_and_b32 s34, s19, 3
	s_add_i32 s5, s4, s5
	s_ashr_i32 s35, s5, 6
	s_lshl_b32 s90, s1, 6
	s_lshl_b32 s5, s1, 13
	s_lshl_b32 s91, s34, 5
	s_lshl_b32 s19, s34, 12
	s_lshl_b64 s[10:11], s[10:11], 2
	v_readlane_b32 s46, v255, 1
	v_readlane_b32 s47, v255, 2
	s_add_u32 s10, s46, s10
	s_addc_u32 s11, s47, s11
	s_and_b64 s[6:7], s[6:7], exec
	s_cselect_b32 s55, s11, 0
	s_cselect_b32 s54, s10, 0
	s_add_u32 s38, s46, 0x1200000
	s_addc_u32 s39, s47, 0
	s_and_b64 s[6:7], s[12:13], exec
	s_cselect_b32 s7, s43, s71
	s_cselect_b32 s6, s42, s70
	s_add_u32 s10, s46, 0x17c00000
	s_addc_u32 s11, s47, 0
	s_add_u32 s23, s46, 0x13c00000
	v_writelane_b32 v254, s6, 54
	s_addc_u32 s36, s47, 0
	v_lshl_add_u64 v[2:3], v[2:3], 0, s[80:81]
	v_writelane_b32 v254, s7, 55
	s_and_b64 s[6:7], s[12:13], exec
	v_readlane_b32 s6, v254, 49
	v_readlane_b32 s7, v254, 50
	s_cselect_b32 s12, s23, s42
	s_cselect_b32 s13, s36, s43
	s_and_b64 s[6:7], s[6:7], exec
	s_cselect_b32 s7, s11, s13
	s_cselect_b32 s6, s10, s12
	v_writelane_b32 v254, s6, 49
	v_readlane_b32 s40, v253, 61
	v_readlane_b32 s41, v253, 62
	v_writelane_b32 v254, s7, 50
	v_readlane_b32 s6, v253, 49
	v_readlane_b32 s7, v253, 50
	s_cselect_b32 s7, s7, s41
	s_cselect_b32 s6, s6, s40
	s_add_u32 s46, s46, s8
	s_addc_u32 s47, s47, s9
	s_add_i32 m0, s44, 0x18000
	s_nop 0
	global_load_lds_dwordx4 v[2:3], off
	v_lshl_add_u64 v[2:3], v[4:5], 0, s[80:81]
	s_add_i32 m0, s44, 0x1a000
	s_add_i32 s36, s44, 0x8000
	global_load_lds_dwordx4 v[2:3], off
	v_lshl_add_u64 v[2:3], v[10:11], 0, s[80:81]
	s_mov_b32 m0, s36
	s_add_i32 s37, s44, 0xa000
	global_load_lds_dwordx4 v[2:3], off
	v_lshl_add_u64 v[2:3], v[12:13], 0, s[80:81]
	s_mov_b32 m0, s37
	v_readlane_b32 s43, v254, 0
	global_load_lds_dwordx4 v[2:3], off
	s_add_i32 m0, s44, 0x1c000
	v_lshl_add_u64 v[2:3], v[6:7], 0, s[80:81]
	global_load_lds_dwordx4 v[2:3], off
	v_lshl_add_u64 v[2:3], v[8:9], 0, s[80:81]
	s_add_i32 m0, s44, 0x1e000
	s_cmp_gt_i32 s4, 63
	global_load_lds_dwordx4 v[2:3], off
	s_waitcnt vmcnt(8)
	s_barrier
	s_cselect_b64 s[48:49], -1, 0
	s_add_i32 s43, s35, -2
	s_cmpk_lt_u32 s0, 0x100
	v_and_b32_e32 v2, 48, v251
	v_lshlrev_b32_e32 v3, 6, v251
	s_movk_i32 s2, 0x3c0
	s_cselect_b64 s[50:51], -1, 0
	s_lshl_b32 s4, s1, 2
	v_and_or_b32 v2, v3, s2, v2
	v_lshlrev_b32_e32 v3, 2, v251
	s_or_b32 s2, s4, s34
	v_writelane_b32 v254, s6, 38
	v_and_b32_e32 v3, 32, v3
	s_cmp_lt_i32 s2, 4
	v_writelane_b32 v254, s7, 39
	v_bitop3_b32 v4, v2, s5, v3 bitop3:0xde
	s_cselect_b64 s[4:5], -1, 0
	v_writelane_b32 v254, s4, 36
	s_and_b32 s0, s0, 0xffffff00
	s_lshl_b32 s41, s3, 3
	v_writelane_b32 v254, s5, 37
	s_lshl_b32 s4, s34, 6
	v_writelane_b32 v254, s2, 44
	s_lshl_b32 s2, s2, 6
	s_or_b32 s0, s4, s0
	v_bitop3_b32 v222, s19, v2, v3 bitop3:0xf6
	v_writelane_b32 v255, s2, 3
	v_writelane_b32 v254, s0, 56
	s_ashr_i32 s40, s84, 31
	s_lshl_b32 s0, s3, 4
	v_cvt_f32_ubyte0_e32 v2, s41
	v_writelane_b32 v255, s54, 4
	s_cmp_lg_u64 s[54:55], 0
	v_rcp_iflag_f32_e32 v2, v2
	v_writelane_b32 v255, s55, 5
	s_cselect_b64 s[54:55], -1, 0
	s_cmp_lg_u32 s73, 0
	v_cvt_f32_u32_e32 v3, s73
	s_cselect_b64 s[56:57], -1, 0
	s_cmp_lg_u64 s[14:15], 0
	v_writelane_b32 v254, s0, 46
	s_cselect_b64 s[58:59], -1, 0
	s_lshl_b32 s0, s1, 8
	s_add_i32 s19, s0, 0
	v_mul_f32_e32 v2, 0x4f7ffffe, v2
	s_add_i32 s19, s19, 0x21c00
	v_cvt_u32_f32_e32 v2, v2
	v_rcp_iflag_f32_e32 v3, v3
	s_cmp_eq_u32 s96, 0
	s_cselect_b64 s[60:61], -1, 0
	s_cmp_eq_u32 s96, 2
	s_cselect_b32 s0, 4, 0
	s_cselect_b32 s1, -4, 0
	s_cmp_eq_u32 s96, 1
	s_cselect_b32 s3, 8, s0
	s_cselect_b32 s0, -8, s1
	v_readfirstlane_b32 s1, v2
	v_mul_f32_e32 v2, 0x4f7ffffe, v3
	v_writelane_b32 v254, s0, 48
	s_sub_i32 s0, 0, s41
	v_cvt_u32_f32_e32 v2, v2
	s_mul_i32 s0, s0, s1
	s_mul_hi_u32 s0, s1, s0
	s_add_i32 s0, s1, s0
	v_writelane_b32 v254, s0, 40
	s_sub_i32 s0, 0, s73
	v_readfirstlane_b32 s1, v2
	v_add_u32_e32 v2, v19, v17
	s_mul_i32 s0, s0, s1
	v_add_lshl_u32 v2, v2, v18, 1
	v_mov_b32_e32 v3, v1
	s_waitcnt vmcnt(6)
	s_mul_hi_u32 s0, s1, s0
	v_lshl_add_u64 v[152:153], s[24:25], 0, v[2:3]
	v_add_u32_e32 v2, v16, v14
	v_readlane_b32 s42, v253, 63
	s_add_i32 s0, s1, s0
	v_add_lshl_u32 v2, v2, v15, 1
	s_mov_b32 s42, 0
	s_mov_b32 s23, s93
	v_writelane_b32 v254, s0, 33
	v_lshl_add_u64 v[154:155], s[24:25], 0, v[2:3]
	v_add_u32_e32 v223, 0, v4
	s_barrier
	s_branch .LBB0_419

; #define PG8_STAGE(bufoff, gbase, voff) do { _Pragma("unroll") for (int _i = 0; _i < 2; ++_i) \
;         __builtin_amdgcn_global_load_lds((const unsigned*)((const char*)(gbase) + (voff)[_i]), (LAS unsigned*)(lds + (bufoff) + ldsw + _i * 8192), 16, 0, 0); } while (0)
; #define PG8_WAIT_V(n) asm volatile("s_waitcnt vmcnt(" #n ")" ::: "memory")
; #define PG8_BAR __builtin_amdgcn_s_barrier()
; template <class Epi>
; __device__ __forceinline__ void gemm_phase(LAS unsigned char* lds, const Gemm g, const StaticOrder& S, const Epi& E, const int tid) {
;     ...
;     PG8_STAGE(PG8_SB(0, 0), cB, voffB); PG8_STAGE(PG8_SB(0, 1), cB + hstepB, voffB); PG8_STAGE(PG8_SA(0, 0), cA, voffA); PG8_STAGE(PG8_SA(0, 1), cA + hstepA, voffA);
;     if (wr == 1) PG8_BAR;
;     PG8_WAIT_V(2); PG8_BAR;
;     PG8_STAGE(PG8_SB(1, 0), cB + kstep, voffB); PG8_STAGE(PG8_SA(1, 0), cA + kstep, voffA); PG8_STAGE(PG8_SB(1, 1), cB + hstepB + kstep, voffB);
;     PG8_WAIT_V(6); PG8_BAR;
.LBB0_641:
	s_lshl_b32 s5, s2, 1
	s_or_b32 s22, s5, 1
	s_ashr_i32 s23, s22, 31
	s_lshl_b64 s[22:23], s[22:23], 21
	s_add_u32 s22, s42, s22
	s_addc_u32 s23, s43, s23
	v_writelane_b32 v254, s22, 51
	s_mul_hi_i32 s5, s2, 0x10800
	v_lshl_add_u64 v[12:13], v[12:13], 0, s[80:81]
	v_writelane_b32 v254, s23, 52
	s_mul_i32 s22, s2, 0x10800
	v_readlane_b32 s24, v254, 1
	v_readlane_b32 s25, v254, 2
	s_add_u32 s22, s24, s22
	v_readlane_b32 s26, v254, 3
	s_addc_u32 s23, s25, s5
	s_mul_i32 s24, s2, 0x5800
	v_readlane_b32 s27, v254, 4
	s_mul_hi_i32 s5, s2, 0x5800
	s_add_u32 s58, s26, s24
	s_addc_u32 s59, s27, s5
	s_add_u32 s60, s42, 0x16c00000
	s_addc_u32 s61, s43, 0
	s_add_i32 m0, s54, 0x18000
	s_nop 0
	global_load_lds_dwordx4 v[12:13], off
	v_lshl_add_u64 v[8:9], v[8:9], 0, s[80:81]
	s_add_i32 m0, s54, 0x1a000
	s_add_i32 s62, s54, 0x8000
	global_load_lds_dwordx4 v[8:9], off
	v_lshl_add_u64 v[8:9], v[10:11], 0, s[80:81]
	s_mov_b32 m0, s62
	s_add_i32 s63, s54, 0xa000
	global_load_lds_dwordx4 v[8:9], off
	v_lshl_add_u64 v[8:9], v[14:15], 0, s[80:81]
	s_mov_b32 m0, s63
	v_lshl_add_u64 v[6:7], v[6:7], 0, s[80:81]
	global_load_lds_dwordx4 v[8:9], off
	s_add_i32 m0, s54, 0x1c000
	v_lshl_add_u64 v[4:5], v[4:5], 0, s[80:81]
	global_load_lds_dwordx4 v[6:7], off
	s_add_i32 m0, s54, 0x1e000
	s_lshr_b32 s7, s7, 26
	global_load_lds_dwordx4 v[4:5], off
	s_waitcnt vmcnt(8)
	s_barrier
	v_and_b32_e32 v4, 48, v251
	v_lshlrev_b32_e32 v5, 6, v251
	s_movk_i32 s2, 0x3c0
	s_add_i32 s7, s6, s7
	v_and_or_b32 v4, v5, s2, v4
	v_lshlrev_b32_e32 v5, 2, v251
	s_and_b32 s5, s21, 3
	s_ashr_i32 s64, s7, 6
	s_lshl_b32 s7, s52, 13
	v_and_b32_e32 v5, 32, v5
	s_lshl_b32 s65, s52, 6
	v_bitop3_b32 v6, v4, s7, v5 bitop3:0xde
	s_lshl_b32 s66, s5, 5
	s_lshl_b32 s7, s5, 12
	s_cmp_gt_i32 s6, 63
	s_cselect_b64 s[24:25], -1, 0
	s_add_i32 s67, s64, -2
	s_cmpk_lt_u32 s20, 0x100
	s_cselect_b64 s[26:27], -1, 0
	s_lshl_b32 s6, s52, 2
	s_or_b32 s68, s6, s5
	s_lshl_b32 s69, s68, 6
	s_cmp_lt_i32 s68, 4
	s_cselect_b64 s[28:29], -1, 0
	s_cmp_gt_i32 s52, 2
	s_cselect_b64 s[30:31], -1, 0
	s_lshl_b32 s5, s52, 11
	s_add_i32 s72, s52, 2
	s_cmp_gt_i32 s52, 0
	s_cselect_b64 s[34:35], -1, 0
	s_lshl_b32 s6, s72, 11
	v_bitop3_b32 v204, s7, v4, v5 bitop3:0xf6
	s_cmp_gt_i32 s52, -2
	v_readlane_b32 s2, v253, 42
	v_add3_u32 v4, v20, v21, v22
	s_cselect_b64 s[36:37], -1, 0
	s_add_i32 s78, s2, s6
	v_mad_u64_u32 v[4:5], s[6:7], s4, v4, v[0:1]
	v_add_lshl_u32 v0, v4, v19, 1
	v_lshl_add_u64 v[188:189], s[0:1], 0, v[0:1]
	v_add3_u32 v0, v16, v17, v18
	s_waitcnt vmcnt(6)
	s_add_i32 s75, s2, s5
	v_mad_u64_u32 v[4:5], s[4:5], s4, v0, v[2:3]
	v_add_lshl_u32 v0, v4, v3, 1
	s_mov_b32 s73, 0
	s_ashr_i32 s74, s84, 31
	s_add_i32 s79, s75, 0xfffff800
	s_add_i32 s85, s78, 0xfffff800
	v_lshl_add_u64 v[190:191], s[0:1], 0, v[0:1]
	v_add_u32_e32 v205, 0, v6
	v_readlane_b32 s83, v253, 43
	s_barrier
	s_branch .LBB0_644
